# prompt-diff work queue split into 4 per-head queues served by workgroups with blockIdx%4==head (XCD-affine K/V streams for L2 locality)
# speedup vs baseline: 1.0061x; 1.0061x over previous
; #define LAS __attribute__((address_space(3)))
; template <int KIND>
; __device__ __forceinline__ void attn_queue(const AttnCtx& C, unsigned* head, int nunits, LAS unsigned char* lds) {
;     volatile LAS unsigned* slot = (volatile LAS unsigned*)(lds + AL_MISC);
;     if constexpr (KIND == 0) tuned::fox_tables(C, lds);
;     for (;;) {
;         __syncthreads();
;         if (threadIdx.x == 0) slot[0] = __hip_atomic_fetch_add(head, 1u, __ATOMIC_RELAXED, __HIP_MEMORY_SCOPE_AGENT);
;         __syncthreads();
;         const unsigned u = slot[0];
;         if (u >= (unsigned)nunits) break;
.LBB0_449:
	s_waitcnt lgkmcnt(0)
	s_barrier
	s_mov_b64 s[2:3], exec
	v_readlane_b32 s0, v253, 26
	v_readlane_b32 s1, v253, 27
	s_and_b64 s[0:1], s[2:3], s[0:1]
	s_mov_b64 exec, s[0:1]
	s_cbranch_execz .LBB0_453
	s_mov_b64 s[6:7], exec
	v_mbcnt_lo_u32_b32 v2, s6, 0
	v_mbcnt_hi_u32_b32 v2, s7, v2
	v_cmp_eq_u32_e32 vcc, 0, v2
	s_and_saveexec_b64 s[4:5], vcc
	s_cbranch_execz .LBB0_452
	v_readlane_b32 s0, v253, 2
	s_and_b32 s0, s0, 3
	s_lshl_b32 s0, s0, 8
	s_add_i32 s0, s0, 0x18000
	v_mov_b32_e32 v254, s0
	s_bcnt1_i32_b64 s0, s[6:7]
	v_mov_b32_e32 v4, s0
	global_atomic_add v4, v254, v4, s[94:95] sc0

; template <bool NOMAX>
; __device__ __forceinline__ void diff_unit(const AttnCtx& C, int u, LAS unsigned char* lds) {
;     int tid = threadIdx.x; asm volatile("" : "+v"(tid));
;     const int lane = tid & 63, r32 = lane & 31, hi = lane >> 5; const int wid = __builtin_amdgcn_readfirstlane(tid >> 6);
;     const int umap = (u >> 2) & 1, h = u & 3, qb = 63 - (u >> 3);
;     const int n = 4 * qb + 4, q0 = 256 * qb;
;     LAS float* wsf = (LAS float*)(lds + TD_WS) + wid * 64;
;     const LAS float* tab = (const LAS float*)(lds + AL_TAB) + h * 192;
;     const float c15 = tab[0];
;     const int qrel = wid * 32 + r32, qpos = q0 + qrel;
;     const int tmax = n - 4 + (wid >> 1);
;     __syncthreads();
;     const bf16* Qw = C.DQ + (size_t)(q0 + wid * 32) * 512 + h * 128 + umap * 64;
;     const bf16* Kh = C.DK + h * 128 + umap * 64; const bf16* Vh = C.DV + h * 128;
;     const unsigned lds0 = (unsigned)(size_t)lds;
;     const bf16* ksrc = Kh + (size_t)lane * 512 + wid * 8;
;     const bf16* vsrc = Vh + (size_t)(16 * (wid & 3) + (lane >> 2)) * 512 + (wid >> 2) * 32 + (lane & 3) * 8;
;     const unsigned kdst = lds0 + TD_K + wid * 1024, vdst = lds0 + TD_V + wid * 1024;
;     ...
;     const lcp kp0 = (lcp)(lds + TD_K) + hi * 1024 + r32 * 16;
; template <int KIND>
; __device__ __forceinline__ void attn_queue(const AttnCtx& C, unsigned* head, int nunits, LAS unsigned char* lds) {
;     ...
;         const unsigned u = slot[0];
;         if (u >= (unsigned)nunits) break;
;         if (KIND == 0) {
;             bool nmx_ = false;
;             if constexpr (KIND == 0) { const int hh_ = (int)u & 7, tr_ = 4 * (63 - ((int)u >> 3)); const LAS float* pr_ = (const LAS float*)(lds + tuned::FX_PRE) + hh_ * tuned::FX_PST; const LAS float* nr_ = (const LAS float*)(lds + tuned::FX_NRM);
;                 const float g_ = (pr_[tr_] - pr_[tr_ + 4]) * LOG2E, b_ = 1.01f * sqrtf((nr_[hh_ * 2] + nr_[hh_ * 2 + 1]) * (nr_[16 + hh_ * 2] + nr_[16 + hh_ * 2 + 1]));
;                 nmx_ = __builtin_amdgcn_readfirstlane((b_ + g_ <= 100.0f) ? 1 : 0) != 0; }
;             if (nmx_) tuned::fox_unit<true>(C, (int)u, lds); else tuned::fox_unit<false>(C, (int)u, lds); } else if (KIND == 1) { if ((C.nomax >> (2 * ((int)u & 3) + (((int)u >> 2) & 1))) & 1) tuned::diff_unit<true>(C, (int)u, lds); else tuned::diff_unit<false>(C, (int)u, lds); } else { if constexpr (KIND == 3) { sample_diff2<0>(C, (int)u, lds);
.LBB0_453:
	s_or_b64 exec, exec, s[2:3]
	s_waitcnt lgkmcnt(0)
	s_barrier
	ds_read_b32 v2, v1
	s_movk_i32 s0, 0x7f
	s_mov_b64 s[2:3], -1
	s_waitcnt lgkmcnt(0)
	v_cmp_lt_u32_e32 vcc, s0, v2
	s_cbranch_vccnz .LBB0_448
	v_readlane_b32 s0, v253, 2
	s_and_b32 s0, s0, 3
	v_lshrrev_b32_e32 v254, 1, v2
	v_and_b32_e32 v2, 1, v2
	v_lshlrev_b32_e32 v2, 2, v2
	v_lshl_or_b32 v2, v254, 3, v2
	v_or_b32_e32 v2, s0, v2
	v_lshlrev_b32_e32 v4, 1, v2
	v_and_b32_e32 v4, 6, v4
	v_bfe_u32 v230, v2, 2, 1
	v_and_b32_e32 v231, 3, v2
	s_movk_i32 s0, 0x300
	v_or_b32_e32 v4, v4, v230
	v_lshrrev_b32_e32 v7, 3, v2
	v_mul_lo_u32 v2, v231, s0
	v_readlane_b32 s0, v253, 56
	v_lshrrev_b32_e32 v4, v4, v233
	v_lshlrev_b32_e32 v220, 8, v231
	v_mov_b32_e32 v221, v3
	v_readlane_b32 s1, v253, 57
	v_and_b32_e32 v6, 1, v4
	v_add_u32_e32 v2, 0, v2
	v_lshl_add_u64 v[4:5], s[0:1], 0, v[220:221]
	v_readlane_b32 s0, v253, 58
	v_xor_b32_e32 v224, 63, v7
	v_add_u32_e32 v235, 0x20400, v2
	v_lshlrev_b32_e32 v8, 7, v231
	v_lshlrev_b32_e32 v9, 6, v230
	v_lshlrev_b32_e32 v2, 7, v230
	v_readlane_b32 s1, v253, 59
	v_cmp_eq_u32_e32 vcc, 0, v6
	v_lshlrev_b32_e32 v234, 2, v224
	v_lshlrev_b32_e32 v19, 8, v224
	v_lshl_add_u64 v[198:199], v[4:5], 0, v[2:3]
	v_lshl_add_u64 v[196:197], s[0:1], 0, v[220:221]
	v_cmp_ne_u32_e64 s[2:3], 63, v7
	v_lshlrev_b32_e32 v218, 1, v8
	v_lshlrev_b32_e32 v200, 1, v9
	s_cbranch_vccnz .LBB0_465
	v_mov_b32_e32 v6, v0
	v_readlane_b32 s4, v253, 54
	v_readfirstlane_b32 s1, v6
	s_ashr_i32 s6, s1, 6
	s_lshl_b32 s33, s6, 5
	v_add_u32_e32 v202, s33, v19
	v_ashrrev_i32_e32 v203, 31, v202
	v_lshlrev_b64 v[4:5], 10, v[202:203]
	v_readlane_b32 s5, v253, 55
	v_and_b32_e32 v212, 63, v6
	v_mov_b32_e32 v219, v3
	v_lshl_add_u64 v[4:5], s[4:5], 0, v[4:5]
	v_lshl_add_u64 v[4:5], v[4:5], 0, v[218:219]
	v_mov_b32_e32 v201, v3
	v_lshlrev_b32_e32 v2, 10, v212
	s_lshl_b32 s0, s6, 4
	v_bfe_u32 v208, v6, 2, 4
	v_lshl_add_u64 v[8:9], v[4:5], 0, v[200:201]
	v_lshl_add_u64 v[4:5], v[198:199], 0, v[2:3]
	s_lshl_b32 s4, s6, 3
	v_and_or_b32 v2, s0, 48, v208
	s_ashr_i32 s5, s4, 31
	v_lshlrev_b32_e32 v2, 10, v2
	s_ashr_i32 s0, s1, 3
	v_lshl_add_u64 v[204:205], s[4:5], 1, v[4:5]
	v_lshl_add_u64 v[4:5], v[196:197], 0, v[2:3]
	s_and_b32 s4, s0, 0xffffffe0
	v_lshlrev_b32_e32 v2, 3, v6
	s_ashr_i32 s5, s4, 31
	v_and_b32_e32 v7, 24, v2
	s_lshl_b32 s49, s6, 10
	v_and_b32_e32 v210, 31, v6
	ds_read_b32 v213, v235
	s_waitcnt lgkmcnt(0)
	s_barrier
	v_lshl_add_u64 v[4:5], s[4:5], 1, v[4:5]
	v_lshlrev_b32_e32 v2, 1, v7
	s_add_i32 s49, s49, 0
	s_mov_b32 s0, m0
	s_mov_b32 m0, s49
	s_nop 0
	global_load_lds_dwordx4 v[204:205], off
	s_mov_b32 m0, s0
	v_bfe_u32 v211, v6, 5, 1
	v_lshl_add_u64 v[4:5], v[4:5], 0, v[2:3]
	s_add_i32 s58, s49, 0x6000
	s_mov_b32 s0, m0
	s_mov_b32 m0, s58
	s_nop 0
	global_load_lds_dwordx4 v[4:5], off
	s_mov_b32 m0, s0
	v_lshlrev_b32_e32 v2, 10, v210
	v_lshl_add_u64 v[10:11], v[4:5], 0, s[18:19]
	s_add_i32 s0, s49, 0x8000
	s_mov_b32 s7, m0
	s_mov_b32 m0, s0
	s_nop 0
	global_load_lds_dwordx4 v[10:11], off
	s_mov_b32 m0, s7
	v_lshl_add_u64 v[8:9], v[8:9], 0, v[2:3]
	v_lshlrev_b32_e32 v2, 4, v211
	v_lshl_add_u64 v[10:11], v[204:205], 0, s[20:21]
	s_add_i32 s0, s49, 0x2000
	s_mov_b32 s7, m0
	s_mov_b32 m0, s0
	s_nop 0
	global_load_lds_dwordx4 v[10:11], off
	s_mov_b32 m0, s7
	v_lshl_add_u64 v[16:17], v[8:9], 0, v[2:3]
	global_load_dwordx4 v[8:11], v[16:17], off
	global_load_dwordx4 v[12:15], v[16:17], off offset:32
	global_load_dwordx4 v[20:23], v[16:17], off offset:64
	global_load_dwordx4 v[24:27], v[16:17], off offset:96
	s_lshl_b32 s0, s6, 12
	s_add_i32 s7, s0, 0
	v_lshlrev_b32_e32 v16, 4, v212
	s_add_i32 s7, s7, 0x12800
	v_add_u32_e32 v219, s7, v16
	v_lshlrev_b32_e32 v201, 10, v211
	v_lshlrev_b32_e32 v2, 4, v210
	s_add_i32 s8, s49, 0x4000
	v_lshl_add_u64 v[16:17], v[204:205], 0, s[22:23]
	v_add3_u32 v222, 0, v201, v2
	s_ashr_i32 s48, s1, 7
	v_or_b32_e32 v2, s33, v210
	s_and_b64 vcc, exec, s[2:3]
	v_add_u32_e32 v223, s48, v234
	v_add_u32_e32 v215, v2, v19
	s_waitcnt vmcnt(3)
	ds_write_b128 v219, v[8:11]
	s_waitcnt vmcnt(2)
	ds_write_b128 v219, v[12:15] offset:1024
	s_waitcnt vmcnt(1)
	ds_write_b128 v219, v[20:23] offset:2048
	s_waitcnt vmcnt(0)
	ds_write_b128 v219, v[24:27] offset:3072
	s_mov_b32 s7, m0
	s_mov_b32 m0, s8
	s_nop 0
	global_load_lds_dwordx4 v[16:17], off
	s_mov_b32 m0, s7
	s_waitcnt vmcnt(4) lgkmcnt(0)
	s_barrier
	ds_read_b128 v[8:11], v222
	ds_read_b128 v[12:15], v219
	s_waitcnt lgkmcnt(0)
	v_mfma_f32_32x32x16_bf16 v[36:51], v[8:11], v[12:15], 0
	ds_read_b128 v[8:11], v222 offset:512
	s_waitcnt lgkmcnt(0)
	v_mfma_f32_32x32x16_bf16 v[20:35], v[8:11], v[12:15], 0
	ds_read_b128 v[8:11], v222 offset:2048
	ds_read_b128 v[12:15], v219 offset:1024
	s_waitcnt lgkmcnt(0)
	v_mfma_f32_32x32x16_bf16 v[36:51], v[8:11], v[12:15], v[36:51]
	ds_read_b128 v[8:11], v222 offset:2560
	s_waitcnt lgkmcnt(0)
	v_mfma_f32_32x32x16_bf16 v[20:35], v[8:11], v[12:15], v[20:35]
	ds_read_b128 v[8:11], v222 offset:4096
	ds_read_b128 v[12:15], v219 offset:2048
	s_waitcnt lgkmcnt(0)
	v_mfma_f32_32x32x16_bf16 v[36:51], v[8:11], v[12:15], v[36:51]
	ds_read_b128 v[8:11], v222 offset:4608
	s_waitcnt lgkmcnt(0)
	v_mfma_f32_32x32x16_bf16 v[20:35], v[8:11], v[12:15], v[20:35]
	ds_read_b128 v[8:11], v222 offset:6144
	ds_read_b128 v[12:15], v219 offset:3072
	s_waitcnt lgkmcnt(0)
	v_mfma_f32_32x32x16_bf16 v[36:51], v[8:11], v[12:15], v[36:51]
	ds_read_b128 v[8:11], v222 offset:6656
	s_waitcnt lgkmcnt(0)
	v_mfma_f32_32x32x16_bf16 v[20:35], v[8:11], v[12:15], v[20:35]
	s_cbranch_vccnz .LBB0_461
; #define TMX3(a, b, c) __builtin_fmaxf(__builtin_fmaxf((a), (b)), (c))
; #define TEX(v) __builtin_amdgcn_exp2f(v)
; #define NEARK(P0, P1, kk) do { if ((kk) >= 62) _Pragma("unroll") for (int r_ = 0; r_ < 16; ++r_) { const int rel0 = (kk) * 64 + crow(r_, hi) - qpos; int i0 = rel0 < -128 ? -128 : rel0; i0 = i0 > 63 ? 63 : i0; int i1 = rel0 + 32 < -128 ? -128 : rel0 + 32; i1 = i1 > 63 ? 63 : i1; \
;             P0[r_] += tab[i0 + 128] - c15; P1[r_] += tab[i1 + 128] - c15; } } while (0)
; template <bool NOMAX>
; __device__ __forceinline__ void diff_unit(const AttnCtx& C, int u, LAS unsigned char* lds) {
;     ...
;         NEARK(pA0, pA1, 0);
;         if constexpr (NOMAX) {
; #pragma unroll
;             for (int r = 0; r < 16; ++r) { pA0[r] = TEX(pA0[r]); pA1[r] = TEX(pA1[r]); }
;         } else {
;         float rm = TMX3(pA0[0], pA0[1], pA1[0]);
; #pragma unroll
;         for (int r = 1; r < 16; ++r) rm = TMX3(rm, pA0[r], pA1[r]);
;         { auto rr = __builtin_amdgcn_permlane32_swap(__float_as_uint(rm), __float_as_uint(rm), false, false); rm = __builtin_fmaxf(__uint_as_float(rr[0]), __uint_as_float(rr[1])); }
;         nm -= rm;
; #pragma unroll
;         for (int r = 0; r < 16; ++r) { pA0[r] = TEX(pA0[r] - rm); pA1[r] = TEX(pA1[r] - rm); }
	v_cmp_gt_i32_e32 vcc, 0, v223
	v_mov_b32_e32 v2, 0xff800000
	s_and_b64 vcc, exec, vcc
	v_mov_b32_e32 v8, 0xff800000
	v_mov_b32_e32 v9, 0xff800000
	v_mov_b32_e32 v10, 0xff800000
	v_mov_b32_e32 v11, 0xff800000
	v_mov_b32_e32 v12, 0xff800000
	v_mov_b32_e32 v13, 0xff800000
	v_mov_b32_e32 v14, 0xff800000
	v_mov_b32_e32 v15, 0xff800000
	v_mov_b32_e32 v16, 0xff800000
	v_mov_b32_e32 v17, 0xff800000
	v_mov_b32_e32 v52, 0xff800000
	v_mov_b32_e32 v53, 0xff800000
	v_mov_b32_e32 v54, 0xff800000
	v_mov_b32_e32 v55, 0xff800000
	v_mov_b32_e32 v56, 0xff800000
	v_mov_b32_e32 v57, 0xff800000
	v_mov_b32_e32 v58, 0xff800000
	v_mov_b32_e32 v59, 0xff800000
	v_mov_b32_e32 v60, 0xff800000
	v_mov_b32_e32 v61, 0xff800000
	v_mov_b32_e32 v62, 0xff800000
	v_mov_b32_e32 v63, 0xff800000
	v_mov_b32_e32 v64, 0xff800000
	v_mov_b32_e32 v65, 0xff800000
	v_mov_b32_e32 v66, 0xff800000
	v_mov_b32_e32 v67, 0xff800000
	v_mov_b32_e32 v68, 0xff800000
	v_mov_b32_e32 v69, 0xff800000
	v_mov_b32_e32 v70, 0xff800000
	v_mov_b32_e32 v71, 0xff800000
	v_mov_b32_e32 v72, 0xff800000
	s_cbranch_vccnz .LBB0_460
	s_cmp_gt_i32 s6, 5
	s_cbranch_scc1 .LBB0_459
	v_lshlrev_b32_e32 v2, 2, v211
	v_sub_u32_e32 v2, v2, v215
	v_add_u32_e32 v10, 1, v2
	v_add_u32_e32 v12, 2, v2
	v_add_u32_e32 v14, 3, v2
	v_med3_i32 v8, v2, s51, 63
	v_med3_i32 v9, v2, s52, 31
	v_med3_i32 v11, v10, s51, 63
	v_med3_i32 v10, v10, s52, 31
	v_med3_i32 v13, v12, s51, 63
	v_med3_i32 v12, v12, s52, 31
	v_med3_i32 v15, v14, s51, 63
	v_med3_i32 v14, v14, s52, 31
	v_lshl_add_u32 v8, v8, 2, v235
	v_lshl_add_u32 v9, v9, 2, v235
	v_lshl_add_u32 v11, v11, 2, v235
	v_lshl_add_u32 v10, v10, 2, v235
	v_lshl_add_u32 v12, v12, 2, v235
	v_lshl_add_u32 v14, v14, 2, v235
	v_lshl_add_u32 v13, v13, 2, v235
	v_lshl_add_u32 v15, v15, 2, v235
	ds_read_b32 v8, v8 offset:512
	ds_read_b32 v58, v9 offset:640
	ds_read_b32 v9, v11 offset:512
	ds_read_b32 v59, v10 offset:640
	ds_read_b32 v10, v13 offset:512
	ds_read_b32 v60, v12 offset:640
	ds_read_b32 v11, v15 offset:512
	ds_read_b32 v61, v14 offset:640
	v_add_u32_e32 v12, 8, v2
	v_add_u32_e32 v14, 9, v2
	v_add_u32_e32 v16, 10, v2
	v_add_u32_e32 v52, 11, v2
	v_med3_i32 v13, v12, s51, 63
	v_med3_i32 v12, v12, s52, 31
	v_med3_i32 v15, v14, s51, 63
	v_med3_i32 v14, v14, s52, 31
	v_med3_i32 v17, v16, s51, 63
	v_med3_i32 v53, v52, s51, 63
	v_lshl_add_u32 v13, v13, 2, v235
	v_lshl_add_u32 v12, v12, 2, v235
	v_lshl_add_u32 v15, v15, 2, v235
	v_lshl_add_u32 v14, v14, 2, v235
	v_med3_i32 v16, v16, s52, 31
	v_lshl_add_u32 v17, v17, 2, v235
	v_med3_i32 v52, v52, s52, 31
	v_lshl_add_u32 v53, v53, 2, v235
	v_lshl_add_u32 v16, v16, 2, v235
	v_lshl_add_u32 v52, v52, 2, v235
	ds_read_b32 v54, v13 offset:512
	ds_read_b32 v62, v12 offset:640
	ds_read_b32 v12, v15 offset:512
	ds_read_b32 v63, v14 offset:640
	ds_read_b32 v14, v17 offset:512
	ds_read_b32 v64, v16 offset:640
	ds_read_b32 v15, v53 offset:512
	ds_read_b32 v65, v52 offset:640
	v_add_u32_e32 v13, 16, v2
	v_add_u32_e32 v17, 17, v2
	v_add_u32_e32 v53, 18, v2
	v_med3_i32 v16, v13, s51, 63
	v_med3_i32 v13, v13, s52, 31
	v_med3_i32 v52, v17, s51, 63
	v_med3_i32 v55, v53, s51, 63
	v_med3_i32 v53, v53, s52, 31
	v_add_u32_e32 v56, 19, v2
	v_lshl_add_u32 v16, v16, 2, v235
	v_lshl_add_u32 v13, v13, 2, v235
	v_med3_i32 v17, v17, s52, 31
	v_lshl_add_u32 v52, v52, 2, v235
	v_lshl_add_u32 v55, v55, 2, v235
	v_lshl_add_u32 v53, v53, 2, v235
	v_med3_i32 v57, v56, s51, 63
	v_med3_i32 v56, v56, s52, 31
	v_lshl_add_u32 v17, v17, 2, v235
	v_lshl_add_u32 v57, v57, 2, v235
	v_lshl_add_u32 v56, v56, 2, v235
	ds_read_b32 v16, v16 offset:512
	ds_read_b32 v66, v13 offset:640
	ds_read_b32 v52, v52 offset:512
	ds_read_b32 v67, v17 offset:640
	ds_read_b32 v55, v55 offset:512
	ds_read_b32 v68, v53 offset:640
	ds_read_b32 v53, v57 offset:512
	ds_read_b32 v69, v56 offset:640
	v_add_u32_e32 v13, 24, v2
	v_med3_i32 v17, v13, s51, 63
	v_med3_i32 v13, v13, s52, 31
	v_lshl_add_u32 v57, v13, 2, v235
	v_add_u32_e32 v13, 25, v2
	v_lshl_add_u32 v56, v17, 2, v235
	v_med3_i32 v17, v13, s51, 63
	v_med3_i32 v13, v13, s52, 31
	v_lshl_add_u32 v71, v13, 2, v235
	v_add_u32_e32 v13, 26, v2
	v_lshl_add_u32 v70, v17, 2, v235
	v_med3_i32 v17, v13, s51, 63
	v_med3_i32 v13, v13, s52, 31
	v_add_u32_e32 v2, 27, v2
	v_lshl_add_u32 v73, v13, 2, v235
	v_med3_i32 v13, v2, s51, 63
	v_med3_i32 v2, v2, s52, 31
	v_lshl_add_u32 v2, v2, 2, v235
	v_lshl_add_u32 v72, v17, 2, v235
	v_lshl_add_u32 v74, v13, 2, v235
	s_waitcnt lgkmcnt(13)
	v_sub_f32_e32 v13, v12, v213
	v_sub_f32_e32 v12, v54, v213
	s_waitcnt lgkmcnt(5)
	v_sub_f32_e32 v17, v52, v213
	s_waitcnt lgkmcnt(3)
	v_sub_f32_e32 v52, v55, v213
	ds_read_b32 v54, v56 offset:512
	ds_read_b32 v75, v57 offset:640
	ds_read_b32 v55, v70 offset:512
	ds_read_b32 v70, v71 offset:640
	ds_read_b32 v56, v72 offset:512
	ds_read_b32 v57, v74 offset:512
	ds_read_b32 v2, v2 offset:640
	ds_read_b32 v71, v73 offset:640
	v_sub_f32_e32 v8, v8, v213
	v_sub_f32_e32 v9, v9, v213
	v_sub_f32_e32 v11, v11, v213
	v_sub_f32_e32 v10, v10, v213
	v_sub_f32_e32 v15, v15, v213
	v_sub_f32_e32 v14, v14, v213
	v_sub_f32_e32 v16, v16, v213
	s_waitcnt lgkmcnt(9)
	v_sub_f32_e32 v53, v53, v213
	s_waitcnt lgkmcnt(5)
	v_sub_f32_e32 v55, v55, v213
	v_sub_f32_e32 v54, v54, v213
	s_waitcnt lgkmcnt(2)
	v_sub_f32_e32 v57, v57, v213
	v_sub_f32_e32 v56, v56, v213
	v_pk_add_f32 v[50:51], v[50:51], v[56:57]
	v_pk_add_f32 v[48:49], v[48:49], v[54:55]
	v_pk_add_f32 v[46:47], v[46:47], v[52:53]
	v_pk_add_f32 v[44:45], v[44:45], v[16:17]
	v_pk_add_f32 v[42:43], v[42:43], v[14:15]
	v_pk_add_f32 v[40:41], v[40:41], v[12:13]
	v_pk_add_f32 v[38:39], v[38:39], v[10:11]
	v_pk_add_f32 v[36:37], v[36:37], v[8:9]
	v_sub_f32_e32 v8, v58, v213
	v_sub_f32_e32 v9, v59, v213
	v_sub_f32_e32 v11, v61, v213
	v_sub_f32_e32 v10, v60, v213
	v_sub_f32_e32 v13, v63, v213
	v_sub_f32_e32 v12, v62, v213
	v_sub_f32_e32 v15, v65, v213
	v_sub_f32_e32 v14, v64, v213
	v_sub_f32_e32 v17, v67, v213
	v_sub_f32_e32 v16, v66, v213
	v_sub_f32_e32 v53, v69, v213
	v_sub_f32_e32 v52, v68, v213
	v_sub_f32_e32 v55, v70, v213
	v_sub_f32_e32 v54, v75, v213
	s_waitcnt lgkmcnt(1)
	v_sub_f32_e32 v57, v2, v213
	s_waitcnt lgkmcnt(0)
	v_sub_f32_e32 v56, v71, v213
	v_pk_add_f32 v[34:35], v[34:35], v[56:57]
	v_pk_add_f32 v[32:33], v[32:33], v[54:55]
	v_pk_add_f32 v[30:31], v[30:31], v[52:53]
	v_pk_add_f32 v[28:29], v[28:29], v[16:17]
	v_pk_add_f32 v[26:27], v[26:27], v[14:15]
	v_pk_add_f32 v[24:25], v[24:25], v[12:13]
	v_pk_add_f32 v[22:23], v[22:23], v[10:11]
	v_pk_add_f32 v[20:21], v[20:21], v[8:9]

; __global__ void __launch_bounds__(NWAVES * 64, LBW) fwd_kernel(Args A) {
	.amdhsa_kernel _Z10fwd_kernel4Args
		.amdhsa_group_segment_fixed_size 0
		.amdhsa_private_segment_fixed_size 0
		.amdhsa_kernarg_size 416
		.amdhsa_user_sgpr_count 2
		.amdhsa_user_sgpr_dispatch_ptr 0
		.amdhsa_user_sgpr_queue_ptr 0
		.amdhsa_user_sgpr_kernarg_segment_ptr 1
		.amdhsa_user_sgpr_dispatch_id 0
		.amdhsa_user_sgpr_kernarg_preload_length 0
		.amdhsa_user_sgpr_kernarg_preload_offset 0
		.amdhsa_user_sgpr_private_segment_size 0
		.amdhsa_uses_dynamic_stack 0
		.amdhsa_enable_private_segment 0
		.amdhsa_system_sgpr_workgroup_id_x 1
		.amdhsa_system_sgpr_workgroup_id_y 0
		.amdhsa_system_sgpr_workgroup_id_z 0
		.amdhsa_system_sgpr_workgroup_info 0
		.amdhsa_system_vgpr_workitem_id 0
		.amdhsa_next_free_vgpr 256
		.amdhsa_next_free_sgpr 98
		.amdhsa_accum_offset 256
		.amdhsa_reserve_vcc 1
		.amdhsa_float_round_mode_32 0
		.amdhsa_float_round_mode_16_64 0
		.amdhsa_float_denorm_mode_32 3
		.amdhsa_float_denorm_mode_16_64 3
		.amdhsa_dx10_clamp 1
		.amdhsa_ieee_mode 1
		.amdhsa_fp16_overflow 0
		.amdhsa_tg_split 0
		.amdhsa_exception_fp_ieee_invalid_op 0
		.amdhsa_exception_fp_denorm_src 0
		.amdhsa_exception_fp_ieee_div_zero 0
		.amdhsa_exception_fp_ieee_overflow 0
		.amdhsa_exception_fp_ieee_underflow 0
		.amdhsa_exception_fp_ieee_inexact 0
		.amdhsa_exception_int_div_zero 0
	.end_amdhsa_kernel

; __global__ void __launch_bounds__(NWAVES * 64, LBW) fwd_kernel(Args A) {
amdhsa.kernels:
  - .agpr_count:     0
    .args:
      - .offset:         0
        .size:           160
        .value_kind:     by_value
      - .offset:         160
        .size:           4
        .value_kind:     hidden_block_count_x
      - .offset:         164
        .size:           4
        .value_kind:     hidden_block_count_y
      - .offset:         168
        .size:           4
        .value_kind:     hidden_block_count_z
      - .offset:         172
        .size:           2
        .value_kind:     hidden_group_size_x
      - .offset:         174
        .size:           2
        .value_kind:     hidden_group_size_y
      - .offset:         176
        .size:           2
        .value_kind:     hidden_group_size_z
      - .offset:         178
        .size:           2
        .value_kind:     hidden_remainder_x
      - .offset:         180
        .size:           2
        .value_kind:     hidden_remainder_y
      - .offset:         182
        .size:           2
        .value_kind:     hidden_remainder_z
      - .offset:         200
        .size:           8
        .value_kind:     hidden_global_offset_x
      - .offset:         208
        .size:           8
        .value_kind:     hidden_global_offset_y
      - .offset:         216
        .size:           8
        .value_kind:     hidden_global_offset_z
      - .offset:         224
        .size:           2
        .value_kind:     hidden_grid_dims
      - .offset:         280
        .size:           4
        .value_kind:     hidden_dynamic_lds_size
    .group_segment_fixed_size: 0
    .kernarg_segment_align: 8
    .kernarg_segment_size: 416
    .language:       OpenCL C
    .language_version:
      - 2
      - 0
    .max_flat_workgroup_size: 512
    .name:           _Z10fwd_kernel4Args
    .private_segment_fixed_size: 0
    .sgpr_count:     104
    .sgpr_spill_count: 128
    .symbol:         _Z10fwd_kernel4Args.kd
    .uniform_work_group_size: 1
    .uses_dynamic_stack: false
    .vgpr_count:     256
    .vgpr_spill_count: 0
    .wavefront_size: 64
